# halo fix-up loop loads up front + split-K reduction reads batched in the out/down and in-proj sample GEMMs + small_gemm128 epilogue loads hoisted
# speedup vs baseline: 1.0057x; 1.0019x over previous
.LBB0_262:
	s_and_b32 s4, s14, 0xffffff00
	s_and_b32 s5, s12, 0x70
	s_or_b32 s4, s4, s5
	v_or_b32_e32 v22, s4, v5
	v_ashrrev_i32_e32 v23, 31, v22
	v_lshlrev_b64 v[22:23], 11, v[22:23]
	v_lshl_add_u64 v[150:151], v[58:59], 0, v[22:23]
	v_add_co_u32_e32 v120, vcc, 0x40000, v150
	global_load_dwordx4 v[6:9], v[60:61], off
	global_load_dwordx4 v[10:13], v[62:63], off
	global_load_dwordx4 v[14:17], v[2:3], off
	global_load_dwordx4 v[18:21], v[2:3], off offset:64
	global_load_dwordx4 v[22:25], v[150:151], off
	global_load_dwordx4 v[26:29], v[150:151], off offset:64
	global_load_dwordx4 v[34:37], v[64:65], off
	global_load_dwordx4 v[42:45], v[66:67], off
	v_addc_co_u32_e32 v121, vcc, 0, v151, vcc
	global_load_dwordx4 v[50:53], v[120:121], off
	global_load_dwordx4 v[54:57], v[120:121], off offset:64
	s_add_i32 s16, s16, s90
	s_add_i32 s14, s14, s15
	s_waitcnt vmcnt(0) lgkmcnt(0)
	v_mfma_f32_16x16x32_bf16 v[30:33], v[22:25], v[14:17], 0
	global_load_dwordx4 v[126:129], v[70:71], off
	v_mfma_f32_16x16x32_bf16 v[38:41], v[22:25], v[6:9], 0
	v_mfma_f32_16x16x32_bf16 v[46:49], v[22:25], v[10:13], 0
	v_mfma_f32_16x16x32_bf16 v[22:25], v[22:25], v[34:37], 0
	v_mfma_f32_16x16x32_bf16 v[14:17], v[50:53], v[14:17], 0
	v_mfma_f32_16x16x32_bf16 v[6:9], v[50:53], v[6:9], 0
	v_mfma_f32_16x16x32_bf16 v[10:13], v[50:53], v[10:13], 0
	v_mfma_f32_16x16x32_bf16 v[34:37], v[50:53], v[34:37], 0
	global_load_dwordx4 v[50:53], v[68:69], off
	v_mfma_f32_16x16x32_bf16 v[30:33], v[26:29], v[18:21], v[30:33]
	v_mfma_f32_16x16x32_bf16 v[38:41], v[26:29], v[42:45], v[38:41]
	v_mfma_f32_16x16x32_bf16 v[14:17], v[54:57], v[18:21], v[14:17]
	v_mfma_f32_16x16x32_bf16 v[6:9], v[54:57], v[42:45], v[6:9]
	s_waitcnt vmcnt(0) lgkmcnt(0)
	v_mfma_f32_16x16x32_bf16 v[46:49], v[26:29], v[50:53], v[46:49]
	v_mfma_f32_16x16x32_bf16 v[22:25], v[26:29], v[126:129], v[22:25]
	global_load_dwordx4 v[18:21], v[72:73], off
	global_load_dwordx4 v[26:29], v[2:3], off offset:128
	global_load_dwordx4 v[42:45], v[2:3], off offset:192
	v_mfma_f32_16x16x32_bf16 v[10:13], v[54:57], v[50:53], v[10:13]
	v_mfma_f32_16x16x32_bf16 v[34:37], v[54:57], v[126:129], v[34:37]
	global_load_dwordx4 v[50:53], v[150:151], off offset:128
	global_load_dwordx4 v[54:57], v[150:151], off offset:192
	global_load_dwordx4 v[126:129], v[74:75], off
	global_load_dwordx4 v[130:133], v[76:77], off
	global_load_dwordx4 v[134:137], v[78:79], off
	s_waitcnt vmcnt(0) lgkmcnt(0)
	v_mfma_f32_16x16x32_bf16 v[30:33], v[50:53], v[26:29], v[30:33]
	v_mfma_f32_16x16x32_bf16 v[38:41], v[50:53], v[18:21], v[38:41]
	v_mfma_f32_16x16x32_bf16 v[46:49], v[50:53], v[126:129], v[46:49]
	v_mfma_f32_16x16x32_bf16 v[22:25], v[50:53], v[130:133], v[22:25]
	global_load_dwordx4 v[50:53], v[120:121], off offset:128
	global_load_dwordx4 v[138:141], v[120:121], off offset:192
	s_waitcnt vmcnt(0) lgkmcnt(0)
	v_mfma_f32_16x16x32_bf16 v[14:17], v[50:53], v[26:29], v[14:17]
	v_mfma_f32_16x16x32_bf16 v[6:9], v[50:53], v[18:21], v[6:9]
	v_mfma_f32_16x16x32_bf16 v[18:21], v[50:53], v[130:133], v[34:37]
	v_mfma_f32_16x16x32_bf16 v[26:29], v[54:57], v[42:45], v[30:33]
	s_nop 2
	global_load_dwordx4 v[30:33], v[80:81], off
	v_mfma_f32_16x16x32_bf16 v[34:37], v[54:57], v[134:137], v[38:41]
	s_nop 2
	global_load_dwordx4 v[38:41], v[82:83], off
	v_mfma_f32_16x16x32_bf16 v[10:13], v[50:53], v[126:129], v[10:13]
	s_waitcnt vmcnt(0) lgkmcnt(0)
	v_mfma_f32_16x16x32_bf16 v[46:49], v[54:57], v[30:33], v[46:49]
	v_mfma_f32_16x16x32_bf16 v[22:25], v[54:57], v[38:41], v[22:25]
	v_mfma_f32_16x16x32_bf16 v[14:17], v[138:141], v[42:45], v[14:17]
	v_mfma_f32_16x16x32_bf16 v[10:13], v[138:141], v[30:33], v[10:13]
	global_load_dwordx4 v[30:33], v[84:85], off
	global_load_dwordx4 v[42:45], v[2:3], off offset:256
	global_load_dwordx4 v[50:53], v[2:3], off offset:320
	v_mfma_f32_16x16x32_bf16 v[18:21], v[138:141], v[38:41], v[18:21]
	global_load_dwordx4 v[38:41], v[150:151], off offset:256
	global_load_dwordx4 v[54:57], v[150:151], off offset:320
	global_load_dwordx4 v[126:129], v[86:87], off
	v_mfma_f32_16x16x32_bf16 v[6:9], v[138:141], v[134:137], v[6:9]
	global_load_dwordx4 v[130:133], v[88:89], off
	global_load_dwordx4 v[134:137], v[90:91], off
	s_waitcnt vmcnt(0) lgkmcnt(0)
	v_mfma_f32_16x16x32_bf16 v[26:29], v[38:41], v[42:45], v[26:29]
	v_mfma_f32_16x16x32_bf16 v[34:37], v[38:41], v[30:33], v[34:37]
	v_mfma_f32_16x16x32_bf16 v[46:49], v[38:41], v[126:129], v[46:49]
	v_mfma_f32_16x16x32_bf16 v[22:25], v[38:41], v[130:133], v[22:25]
	global_load_dwordx4 v[38:41], v[120:121], off offset:256
	global_load_dwordx4 v[138:141], v[120:121], off offset:320
	s_waitcnt vmcnt(0) lgkmcnt(0)
	v_mfma_f32_16x16x32_bf16 v[6:9], v[38:41], v[30:33], v[6:9]
	global_load_dwordx4 v[30:33], v[92:93], off
	v_mfma_f32_16x16x32_bf16 v[10:13], v[38:41], v[126:129], v[10:13]
	global_load_dwordx4 v[126:129], v[94:95], off
	v_mfma_f32_16x16x32_bf16 v[14:17], v[38:41], v[42:45], v[14:17]
	v_mfma_f32_16x16x32_bf16 v[18:21], v[38:41], v[130:133], v[18:21]
	v_mfma_f32_16x16x32_bf16 v[26:29], v[54:57], v[50:53], v[26:29]
	v_mfma_f32_16x16x32_bf16 v[42:45], v[54:57], v[134:137], v[34:37]
	s_waitcnt vmcnt(0) lgkmcnt(0)
	v_mfma_f32_16x16x32_bf16 v[130:133], v[54:57], v[30:33], v[46:49]
	v_mfma_f32_16x16x32_bf16 v[142:145], v[54:57], v[126:129], v[22:25]
	global_load_dwordx4 v[54:57], v[96:97], off
	v_mfma_f32_16x16x32_bf16 v[146:149], v[138:141], v[50:53], v[14:17]
	v_mfma_f32_16x16x32_bf16 v[50:53], v[138:141], v[134:137], v[6:9]
	v_mfma_f32_16x16x32_bf16 v[34:37], v[138:141], v[30:33], v[10:13]
	global_load_dwordx4 v[38:41], v[98:99], off
	global_load_dwordx4 v[134:137], v[2:3], off offset:384
	s_nop 0
	global_load_dwordx4 v[10:13], v[2:3], off offset:448
	v_mfma_f32_16x16x32_bf16 v[30:33], v[138:141], v[126:129], v[18:21]
	global_load_dwordx4 v[126:129], v[150:151], off offset:384
	global_load_dwordx4 v[22:25], v[150:151], off offset:448
	global_load_dwordx4 v[46:49], v[100:101], off
	global_load_dwordx4 v[18:21], v[102:103], off
	global_load_dwordx4 v[14:17], v[104:105], off
	global_load_dwordx4 v[6:9], v[106:107], off
	global_load_dwordx4 v[138:141], v[120:121], off offset:384
	s_waitcnt vmcnt(0) lgkmcnt(0)
	v_mfma_f32_16x16x32_bf16 v[26:29], v[126:129], v[134:137], v[26:29]
	v_add_u32_e32 v150, s12, v124
	v_ashrrev_i32_e32 v151, 31, v150
	s_add_i32 s12, s12, s13
	v_mfma_f32_16x16x32_bf16 v[42:45], v[126:129], v[54:57], v[42:45]
	s_cmpk_gt_i32 s16, 0xbf
	v_mfma_f32_16x16x32_bf16 v[130:133], v[126:129], v[38:41], v[130:133]
	v_mfma_f32_16x16x32_bf16 v[126:129], v[126:129], v[46:49], v[142:145]
	s_nop 2
	global_load_dwordx4 v[142:145], v[120:121], off offset:448
	v_mfma_f32_16x16x32_bf16 v[134:137], v[138:141], v[134:137], v[146:149]
	v_lshl_add_u64 v[120:121], v[150:151], 1, v[118:119]
	v_mfma_f32_16x16x32_bf16 v[50:53], v[138:141], v[54:57], v[50:53]
	v_lshlrev_b64 v[54:55], 2, v[150:151]
	v_lshl_add_u64 v[56:57], v[110:111], 0, v[54:55]
	v_lshl_add_u64 v[146:147], v[112:113], 0, v[54:55]
	v_mfma_f32_16x16x32_bf16 v[34:37], v[138:141], v[38:41], v[34:37]
	v_add_co_u32_e32 v156, vcc, s19, v56
	v_lshl_add_u64 v[148:149], s[10:11], 0, v[54:55]
	v_mfma_f32_16x16x32_bf16 v[30:33], v[138:141], v[46:49], v[30:33]
	v_addc_co_u32_e32 v157, vcc, 0, v57, vcc
	v_add_co_u32_e32 v158, vcc, s19, v146
	v_mfma_f32_16x16x32_bf16 v[26:29], v[22:25], v[10:13], v[26:29]
	v_lshl_add_u64 v[138:139], s[2:3], 0, v[54:55]
	v_addc_co_u32_e32 v159, vcc, 0, v147, vcc
	v_mfma_f32_16x16x32_bf16 v[38:41], v[22:25], v[18:21], v[42:45]
	v_add_co_u32_e32 v160, vcc, s19, v138
	v_lshl_add_u64 v[140:141], s[8:9], 0, v[54:55]
	v_mfma_f32_16x16x32_bf16 v[42:45], v[22:25], v[14:17], v[130:133]
	v_addc_co_u32_e32 v161, vcc, 0, v139, vcc
	v_add_co_u32_e32 v162, vcc, s19, v140
	v_mfma_f32_16x16x32_bf16 v[22:25], v[22:25], v[6:9], v[126:129]
	s_nop 0
	v_addc_co_u32_e32 v163, vcc, 0, v141, vcc
	v_add_co_u32_e32 v164, vcc, s19, v148
	s_waitcnt vmcnt(0) lgkmcnt(0)
	v_mfma_f32_16x16x32_bf16 v[10:13], v[142:145], v[10:13], v[134:137]
	v_lshl_add_u64 v[150:151], s[6:7], 0, v[54:55]
	v_addc_co_u32_e32 v165, vcc, 0, v149, vcc
	v_mfma_f32_16x16x32_bf16 v[18:21], v[142:145], v[18:21], v[50:53]
	v_add_co_u32_e32 v166, vcc, s19, v150
	v_lshl_add_u64 v[152:153], v[114:115], 0, v[54:55]
	v_mfma_f32_16x16x32_bf16 v[14:17], v[142:145], v[14:17], v[34:37]
	v_addc_co_u32_e32 v167, vcc, 0, v151, vcc
	v_lshl_add_u64 v[154:155], v[116:117], 0, v[54:55]
	v_mfma_f32_16x16x32_bf16 v[6:9], v[142:145], v[6:9], v[30:33]
	ds_write_b128 v0, v[26:29]
	ds_write_b128 v0, v[38:41] offset:2048
	ds_write_b128 v0, v[42:45] offset:4096
	ds_write_b128 v0, v[22:25] offset:6144
	ds_write_b128 v0, v[10:13] offset:1024
	ds_write_b128 v0, v[18:21] offset:3072
	ds_write_b128 v0, v[14:17] offset:5120
	s_nop 0
	ds_write_b128 v0, v[6:9] offset:7168
	s_waitcnt lgkmcnt(0)
	s_barrier
	s_nop 1
	global_load_dwordx4 v[208:211], v[166:167], off
	s_nop 1
	global_load_dwordx4 v[204:207], v[164:165], off
	s_nop 1
	global_load_dwordx4 v[200:203], v[160:161], off
	s_nop 1
	global_load_dwordx4 v[192:195], v[156:157], off nt
	s_nop 1
	global_load_dwordx4 v[188:191], v[158:159], off nt
	s_nop 1
	global_load_dwordx4 v[184:187], v[162:163], off
	s_nop 1
	global_load_dwordx4 v[180:183], v[150:151], off
	s_nop 1
	global_load_dwordx4 v[176:179], v[148:149], off
	s_nop 1
	global_load_dwordx4 v[172:175], v[140:141], off
	s_nop 1
	global_load_dwordx4 v[168:171], v[138:139], off
	global_load_dwordx4 v[6:9], v[108:109], off
	global_load_dwordx4 v[10:13], v[108:109], off offset:16
	global_load_dwordx4 v[14:17], v[146:147], off nt
	global_load_dwordx4 v[18:21], v[56:57], off nt
	ds_read_b128 v[22:25], v125
	ds_read_b128 v[26:29], v125 offset:1024
	ds_read_b128 v[30:33], v125 offset:8192
	ds_read_b128 v[34:37], v125 offset:9216
	ds_read_b128 v[38:41], v125 offset:16384
	ds_read_b128 v[42:45], v125 offset:17408
	ds_read_b128 v[46:49], v125 offset:24576
	ds_read_b128 v[50:53], v125 offset:25600
	s_waitcnt lgkmcnt(0)
	v_pk_add_f32 v[22:23], v[22:23], 0 op_sel_hi:[1,0]
	s_waitcnt vmcnt(4)
	s_nop 0
	v_mov_b32_e32 v54, v168
	v_mov_b32_e32 v55, v169
	v_mov_b32_e32 v56, v170
	v_mov_b32_e32 v57, v171
	s_nop 1
	s_waitcnt vmcnt(5)
	s_nop 0
	v_mov_b32_e32 v126, v172
	v_mov_b32_e32 v127, v173
	v_mov_b32_e32 v128, v174
	v_mov_b32_e32 v129, v175
	s_nop 1
	s_waitcnt vmcnt(6)
	s_nop 0
	v_mov_b32_e32 v130, v176
	v_mov_b32_e32 v131, v177
	v_mov_b32_e32 v132, v178
	v_mov_b32_e32 v133, v179
	s_nop 1
	s_waitcnt vmcnt(7)
	s_nop 0
	v_mov_b32_e32 v134, v180
	v_mov_b32_e32 v135, v181
	v_mov_b32_e32 v136, v182
	v_mov_b32_e32 v137, v183
	s_nop 1
	v_pk_add_f32 v[22:23], v[22:23], v[30:31]
	v_pk_add_f32 v[24:25], v[24:25], 0 op_sel_hi:[1,0]
	v_pk_add_f32 v[22:23], v[22:23], v[38:39]
	v_pk_add_f32 v[24:25], v[24:25], v[32:33]
	v_pk_add_f32 v[22:23], v[22:23], v[46:47]
	v_pk_add_f32 v[24:25], v[24:25], v[40:41]
	v_pk_add_f32 v[26:27], v[26:27], 0 op_sel_hi:[1,0]
	v_pk_add_f32 v[24:25], v[24:25], v[48:49]
	v_pk_add_f32 v[26:27], v[26:27], v[34:35]
	v_pk_add_f32 v[28:29], v[28:29], 0 op_sel_hi:[1,0]
	v_pk_add_f32 v[26:27], v[26:27], v[42:43]
	v_pk_add_f32 v[28:29], v[28:29], v[36:37]
	v_pk_add_f32 v[26:27], v[26:27], v[50:51]
	v_pk_add_f32 v[28:29], v[28:29], v[44:45]
	s_waitcnt vmcnt(0)
	v_mov_b32_e32 v30, v6
	v_mov_b32_e32 v31, v10
	v_mov_b32_e32 v10, v7
	v_mov_b32_e32 v6, v8
	v_mov_b32_e32 v7, v12
	v_mov_b32_e32 v12, v9
	v_pk_add_f32 v[8:9], v[30:31], v[10:11]
	v_pk_add_f32 v[6:7], v[6:7], v[12:13]
	global_store_dwordx4 v[152:153], v[14:17], off
	v_pk_add_f32 v[6:7], v[8:9], v[6:7]
	v_pk_add_f32 v[28:29], v[28:29], v[52:53]
	v_add_f32_e32 v6, v6, v7
	ds_bpermute_b32 v7, v122, v6
	s_waitcnt lgkmcnt(0)
	v_pk_mul_f32 v[16:17], v[16:17], v[128:129]
	v_pk_mul_f32 v[14:15], v[14:15], v[126:127]
	v_pk_fma_f32 v[20:21], v[20:21], v[56:57], v[16:17]
	v_pk_fma_f32 v[18:19], v[18:19], v[54:55], v[14:15]
	v_add_f32_e32 v6, v6, v7
	ds_bpermute_b32 v7, v123, v6
	s_waitcnt lgkmcnt(0)
	v_add_f32_e32 v6, v6, v7
	v_fmamk_f32 v6, v6, 0x3a800000, v219
	v_mul_f32_e32 v7, 0x4f800000, v6
	v_cmp_gt_f32_e32 vcc, s85, v6
	s_nop 1
	v_cndmask_b32_e32 v6, v6, v7, vcc
	v_sqrt_f32_e32 v7, v6
	s_nop 0
	v_add_u32_e32 v8, -1, v7
	v_add_u32_e32 v9, 1, v7
	v_fma_f32 v10, -v8, v7, v6
	v_fma_f32 v11, -v9, v7, v6
	v_cmp_ge_f32_e64 s[4:5], 0, v10
	s_nop 1
	v_cndmask_b32_e64 v7, v7, v8, s[4:5]
	v_cmp_lt_f32_e64 s[4:5], 0, v11
	s_nop 1
	v_cndmask_b32_e64 v7, v7, v9, s[4:5]
	v_mul_f32_e32 v8, 0x37800000, v7
	v_cndmask_b32_e32 v7, v7, v8, vcc
	v_cmp_class_f32_e32 vcc, v6, v221
	s_nop 1
	v_cndmask_b32_e32 v6, v7, v6, vcc
	v_div_scale_f32 v7, s[4:5], v6, v6, 1.0
	v_rcp_f32_e32 v9, v7
	v_div_scale_f32 v8, vcc, 1.0, v6, 1.0
	v_fma_f32 v10, -v7, v9, 1.0
	v_fmac_f32_e32 v9, v10, v9
	v_mul_f32_e32 v10, v8, v9
	v_fma_f32 v11, -v7, v10, v8
	v_fmac_f32_e32 v10, v11, v9
	v_fma_f32 v7, -v7, v10, v8
	v_div_fmas_f32 v7, v7, v9, v10
	v_div_fixup_f32 v142, v7, v6, 1.0
	v_pk_mul_f32 v[8:9], v[24:25], v[142:143] op_sel_hi:[1,0]
	v_pk_mul_f32 v[6:7], v[22:23], v[142:143] op_sel_hi:[1,0]
	global_store_dwordx4 v[154:155], v[6:9], off
	s_waitcnt vmcnt(10)
	s_nop 0
	v_mov_b32_e32 v10, v184
	v_mov_b32_e32 v11, v185
	v_mov_b32_e32 v12, v186
	v_mov_b32_e32 v13, v187
	s_nop 1
	s_waitcnt vmcnt(11)
	s_nop 0
	v_mov_b32_e32 v22, v188
	v_mov_b32_e32 v23, v189
	v_mov_b32_e32 v24, v190
	v_mov_b32_e32 v25, v191
	s_nop 1
	s_waitcnt vmcnt(12)
	s_nop 0
	v_mov_b32_e32 v30, v192
	v_mov_b32_e32 v31, v193
	v_mov_b32_e32 v32, v194
	v_mov_b32_e32 v33, v195
	s_nop 1
	s_waitcnt vmcnt(13)
	s_nop 0
	v_mov_b32_e32 v38, v200
	v_mov_b32_e32 v39, v201
	v_mov_b32_e32 v40, v202
	v_mov_b32_e32 v41, v203
	s_nop 1
	s_waitcnt vmcnt(14)
	s_nop 0
	v_mov_b32_e32 v46, v204
	v_mov_b32_e32 v47, v205
	v_mov_b32_e32 v48, v206
	v_mov_b32_e32 v49, v207
	s_nop 1
	s_waitcnt vmcnt(15)
	s_nop 0
	v_mov_b32_e32 v138, v208
	v_mov_b32_e32 v139, v209
	v_mov_b32_e32 v140, v210
	v_mov_b32_e32 v141, v211
	s_nop 1
	v_pk_fma_f32 v[6:7], v[130:131], v[6:7], v[18:19]
	v_pk_fma_f32 v[8:9], v[132:133], v[8:9], v[20:21]
	v_pk_add_f32 v[6:7], v[134:135], v[6:7]
	v_pk_add_f32 v[8:9], v[136:137], v[8:9]
	v_pk_mul_f32 v[14:15], v[26:27], v[142:143] op_sel_hi:[1,0]
	v_mul_f32_e32 v20, v6, v6
	v_mul_f32_e32 v21, v7, v7
	v_mul_f32_e32 v26, v8, v8
	v_mul_f32_e32 v27, v9, v9
	v_fmamk_f32 v20, v20, 0xbdd2d3e2, v220
	v_fmamk_f32 v21, v21, 0xbdd2d3e2, v220
	v_fmamk_f32 v26, v26, 0xbdd2d3e2, v220
	v_fmamk_f32 v27, v27, 0xbdd2d3e2, v220
	v_mov_b32_e32 v18, v6
	v_mul_f32_e32 v6, v6, v20
	v_mul_f32_e32 v20, v7, v21
	v_mul_f32_e32 v21, v8, v26
	v_mul_f32_e32 v26, v9, v27
	v_mov_b32_e32 v19, v8
	v_mov_b32_e32 v8, v7
	v_exp_f32_e32 v7, v20
	v_exp_f32_e32 v20, v21
	v_exp_f32_e32 v21, v26
	v_exp_f32_e32 v6, v6
	v_add_f32_e32 v7, 1.0, v7
	v_add_co_u32_e32 v144, vcc, s19, v152
	v_add_f32_e32 v21, 1.0, v21
	v_add_f32_e32 v6, 1.0, v6
	v_add_f32_e32 v26, 1.0, v20
	v_rcp_f32_e32 v20, v7
	v_rcp_f32_e32 v21, v21
	v_addc_co_u32_e32 v145, vcc, 0, v153, vcc
	v_pk_mul_f32 v[16:17], v[28:29], v[142:143] op_sel_hi:[1,0]
	v_rcp_f32_e32 v6, v6
	v_rcp_f32_e32 v7, v26
	v_add_co_u32_e32 v146, vcc, s19, v154
	v_pk_mul_f32 v[8:9], v[8:9], v[20:21]
	s_nop 0
	v_addc_co_u32_e32 v147, vcc, 0, v155, vcc
	global_store_dwordx4 v[146:147], v[14:17], off
	v_pk_mul_f32 v[6:7], v[18:19], v[6:7]
	s_waitcnt lgkmcnt(0)
	v_pk_mul_f32 v[12:13], v[24:25], v[12:13]
	v_pk_mul_f32 v[10:11], v[22:23], v[10:11]
	v_pk_fma_f32 v[12:13], v[32:33], v[40:41], v[12:13]
	v_pk_fma_f32 v[10:11], v[30:31], v[38:39], v[10:11]
	v_pk_fma_f32 v[12:13], v[16:17], v[48:49], v[12:13]
	v_pk_fma_f32 v[10:11], v[14:15], v[46:47], v[10:11]
	v_pk_add_f32 v[12:13], v[140:141], v[12:13]
	v_pk_add_f32 v[10:11], v[138:139], v[10:11]
	v_mov_b32_e32 v15, v12
	v_mov_b32_e32 v12, v11
	v_mov_b32_e32 v14, v10
	v_pk_mul_f32 v[8:9], v[12:13], v[8:9]
	v_pk_mul_f32 v[6:7], v[14:15], v[6:7]
	v_and_b32_sdwa v12, v9, v218 dst_sel:DWORD dst_unused:UNUSED_PAD src0_sel:WORD_1 src1_sel:DWORD
	v_and_b32_sdwa v13, v8, v218 dst_sel:DWORD dst_unused:UNUSED_PAD src0_sel:WORD_1 src1_sel:DWORD
	v_and_b32_sdwa v10, v7, v218 dst_sel:DWORD dst_unused:UNUSED_PAD src0_sel:WORD_1 src1_sel:DWORD
	v_and_b32_sdwa v11, v6, v218 dst_sel:DWORD dst_unused:UNUSED_PAD src0_sel:WORD_1 src1_sel:DWORD
	v_add3_u32 v9, v9, v12, s91
	v_add3_u32 v8, v8, v13, s91
	v_add3_u32 v6, v6, v11, s91
	v_add3_u32 v7, v7, v10, s91
	v_and_b32_e32 v9, 0xffff0000, v9
	v_and_b32_e32 v8, 0xffff0000, v8
	v_or_b32_sdwa v7, v9, v7 dst_sel:DWORD dst_unused:UNUSED_PAD src0_sel:DWORD src1_sel:WORD_1
	v_or_b32_sdwa v6, v8, v6 dst_sel:DWORD dst_unused:UNUSED_PAD src0_sel:DWORD src1_sel:WORD_1
	global_store_dwordx4 v[144:145], v[22:25], off
	global_store_dwordx2 v[120:121], v[6:7], off
	s_waitcnt lgkmcnt(0)
	s_barrier
	s_cbranch_scc0 .LBB0_262

.LBB0_673:
	s_and_b32 s6, s14, 0xffffffe0
	v_or_b32_e32 v6, s6, v5
	v_ashrrev_i32_e32 v7, 31, v6
	s_and_b32 s4, s12, 0x70
	v_lshlrev_b64 v[6:7], 11, v[6:7]
	v_or_b32_e32 v19, s4, v5
	v_lshl_add_u64 v[40:41], v[14:15], 0, v[6:7]
	s_mov_b32 s4, 0x8000
	v_lshlrev_b32_e32 v0, 11, v19
	v_add_co_u32_e32 v42, vcc, s4, v40
	v_lshl_add_u64 v[38:39], v[2:3], 0, v[0:1]
	s_nop 0
	v_addc_co_u32_e32 v43, vcc, 0, v41, vcc
	global_load_dwordx4 v[6:9], v[38:39], off
	global_load_dwordx4 v[10:13], v[40:41], off
	s_waitcnt lgkmcnt(0)
	global_load_dwordx4 v[22:25], v[42:43], off
	global_load_dwordx4 v[26:29], v[40:41], off offset:64
	global_load_dwordx4 v[30:33], v[38:39], off offset:64
	v_add_u32_e32 v0, s11, v21
	s_andn2_b64 vcc, exec, s[2:3]
	s_waitcnt vmcnt(0)
	v_mfma_f32_16x16x32_bf16 v[10:13], v[10:13], v[6:9], 0
	s_waitcnt lgkmcnt(0)
	v_mfma_f32_16x16x32_bf16 v[6:9], v[22:25], v[6:9], 0
	global_load_dwordx4 v[22:25], v[42:43], off offset:64
	v_mfma_f32_16x16x32_bf16 v[10:13], v[26:29], v[30:33], v[10:13]
	global_load_dwordx4 v[26:29], v[40:41], off offset:128
	global_load_dwordx4 v[34:37], v[38:39], off offset:128
	s_waitcnt vmcnt(0) lgkmcnt(0)
	v_mfma_f32_16x16x32_bf16 v[10:13], v[26:29], v[34:37], v[10:13]
	v_mfma_f32_16x16x32_bf16 v[6:9], v[22:25], v[30:33], v[6:9]
	global_load_dwordx4 v[22:25], v[42:43], off offset:128
	global_load_dwordx4 v[26:29], v[40:41], off offset:192
	global_load_dwordx4 v[30:33], v[42:43], off offset:192
	s_waitcnt vmcnt(0) lgkmcnt(0)
	v_mfma_f32_16x16x32_bf16 v[22:25], v[22:25], v[34:37], v[6:9]
	global_load_dwordx4 v[34:37], v[38:39], off offset:192
	s_waitcnt vmcnt(0) lgkmcnt(0)
	v_mfma_f32_16x16x32_bf16 v[6:9], v[26:29], v[34:37], v[10:13]
	v_mfma_f32_16x16x32_bf16 v[10:13], v[30:33], v[34:37], v[22:25]
	s_nop 6
	ds_write_b128 v0, v[6:9]
	ds_write_b128 v0, v[10:13] offset:1024
	s_waitcnt lgkmcnt(0)
	s_barrier
	s_cbranch_vccnz .LBB0_672
	v_lshlrev_b32_e32 v0, 7, v19
	s_ashr_i32 s7, s6, 31
	ds_read_b128 v[64:67], v21 offset:2048
	ds_read_b128 v[68:71], v21 offset:3072
	ds_read_b128 v[72:75], v21 offset:4096
	ds_read_b128 v[76:79], v21 offset:5120
	ds_read_b128 v[80:83], v21 offset:6144
	ds_read_b128 v[84:87], v21 offset:7168
	ds_read_b128 v[88:91], v21 offset:8192
	ds_read_b128 v[92:95], v21 offset:9216
	ds_read_b128 v[96:99], v21 offset:10240
	ds_read_b128 v[100:103], v21 offset:11264
	ds_read_b128 v[104:107], v21 offset:12288
	ds_read_b128 v[108:111], v21 offset:13312
	ds_read_b128 v[112:115], v21 offset:14336
	ds_read_b128 v[116:119], v21 offset:15360
	s_waitcnt lgkmcnt(13)
	v_pk_add_f32 v[24:25], v[8:9], v[66:67]
	v_pk_add_f32 v[22:23], v[6:7], v[64:65]
	s_waitcnt lgkmcnt(12)
	v_pk_add_f32 v[12:13], v[12:13], v[70:71]
	v_pk_add_f32 v[10:11], v[10:11], v[68:69]
	s_waitcnt lgkmcnt(11)
	v_pk_add_f32 v[24:25], v[24:25], v[74:75]
	v_pk_add_f32 v[22:23], v[22:23], v[72:73]
	s_waitcnt lgkmcnt(10)
	v_pk_add_f32 v[12:13], v[12:13], v[78:79]
	v_pk_add_f32 v[10:11], v[10:11], v[76:77]
	s_waitcnt lgkmcnt(9)
	v_pk_add_f32 v[24:25], v[24:25], v[82:83]
	v_pk_add_f32 v[22:23], v[22:23], v[80:81]
	s_waitcnt lgkmcnt(8)
	v_pk_add_f32 v[12:13], v[12:13], v[86:87]
	v_pk_add_f32 v[10:11], v[10:11], v[84:85]
	s_waitcnt lgkmcnt(7)
	v_pk_add_f32 v[24:25], v[24:25], v[90:91]
	v_pk_add_f32 v[22:23], v[22:23], v[88:89]
	s_waitcnt lgkmcnt(6)
	v_pk_add_f32 v[12:13], v[12:13], v[94:95]
	v_pk_add_f32 v[10:11], v[10:11], v[92:93]
	s_waitcnt lgkmcnt(5)
	v_pk_add_f32 v[24:25], v[24:25], v[98:99]
	v_pk_add_f32 v[22:23], v[22:23], v[96:97]
	s_waitcnt lgkmcnt(4)
	v_pk_add_f32 v[12:13], v[12:13], v[102:103]
	v_pk_add_f32 v[10:11], v[10:11], v[100:101]
	s_waitcnt lgkmcnt(3)
	v_pk_add_f32 v[24:25], v[24:25], v[106:107]
	v_pk_add_f32 v[22:23], v[22:23], v[104:105]
	s_waitcnt lgkmcnt(2)
	v_pk_add_f32 v[12:13], v[12:13], v[110:111]
	v_pk_add_f32 v[26:27], v[10:11], v[108:109]
	s_waitcnt lgkmcnt(1)
	v_pk_add_f32 v[28:29], v[24:25], v[114:115]
	v_pk_add_f32 v[30:31], v[22:23], v[112:113]
	s_waitcnt lgkmcnt(0)
	v_pk_add_f32 v[10:11], v[12:13], v[118:119]
	v_pk_add_f32 v[12:13], v[26:27], v[116:117]
	v_lshl_add_u64 v[22:23], v[16:17], 0, v[0:1]
	global_load_dwordx4 v[6:9], v[22:23], off
	s_nop 0
	global_load_dwordx4 v[22:25], v[22:23], off offset:16
	s_waitcnt vmcnt(0) lgkmcnt(0)
	v_mov_b32_e32 v26, v6
	v_mov_b32_e32 v27, v22
	v_mov_b32_e32 v22, v7
	v_pk_add_f32 v[6:7], v[26:27], v[22:23]
	v_mov_b32_e32 v22, v8
	v_mov_b32_e32 v23, v24
	v_mov_b32_e32 v24, v9
	v_pk_add_f32 v[8:9], v[22:23], v[24:25]
	s_nop 0
	v_pk_add_f32 v[6:7], v[6:7], v[8:9]
	s_nop 0
	v_add_f32_e32 v0, v6, v7
	ds_bpermute_b32 v6, v174, v0
	s_waitcnt lgkmcnt(0)
	v_add_f32_e32 v0, v0, v6
	ds_bpermute_b32 v6, v175, v0
	s_waitcnt lgkmcnt(0)
	v_add_f32_e32 v0, v0, v6
	v_fmamk_f32 v0, v0, 0x3a800000, v219
	v_cmp_gt_f32_e32 vcc, s85, v0
	v_mul_f32_e32 v6, 0x4f800000, v0
	s_nop 0
	v_cndmask_b32_e32 v0, v0, v6, vcc
	v_sqrt_f32_e32 v6, v0
	s_nop 0
	v_add_u32_e32 v7, -1, v6
	v_fma_f32 v8, -v7, v6, v0
	v_cmp_ge_f32_e64 s[4:5], 0, v8
	v_add_u32_e32 v8, 1, v6
	s_nop 0
	v_cndmask_b32_e64 v7, v6, v7, s[4:5]
	v_fma_f32 v6, -v8, v6, v0
	v_cmp_lt_f32_e64 s[4:5], 0, v6
	s_nop 1
	v_cndmask_b32_e64 v6, v7, v8, s[4:5]
	v_mul_f32_e32 v7, 0x37800000, v6
	v_cndmask_b32_e32 v6, v6, v7, vcc
	v_cmp_class_f32_e32 vcc, v0, v221
	s_nop 1
	v_cndmask_b32_e32 v0, v6, v0, vcc
	v_div_scale_f32 v6, s[4:5], v0, v0, 1.0
	v_rcp_f32_e32 v7, v6
	s_nop 0
	v_fma_f32 v8, -v6, v7, 1.0
	v_fmac_f32_e32 v7, v8, v7
	v_div_scale_f32 v8, vcc, 1.0, v0, 1.0
	v_mul_f32_e32 v9, v8, v7
	v_fma_f32 v20, -v6, v9, v8
	v_fmac_f32_e32 v9, v20, v7
	v_fma_f32 v6, -v6, v9, v8
	v_div_fmas_f32 v6, v6, v7, v9
	v_div_fixup_f32 v20, v6, v0, 1.0
	v_mul_u32_u24_e32 v0, 0x700, v19
	v_lshlrev_b32_e32 v0, 2, v0
	v_lshl_add_u64 v[22:23], s[0:1], 0, v[0:1]
	v_lshl_add_u64 v[22:23], s[6:7], 2, v[22:23]
	v_mov_b32_e32 v19, v1
	v_pk_mul_f32 v[8:9], v[28:29], v[20:21] op_sel_hi:[1,0]
	v_pk_mul_f32 v[6:7], v[30:31], v[20:21] op_sel_hi:[1,0]
	v_lshl_add_u64 v[22:23], v[22:23], 0, v[18:19]
	global_store_dwordx4 v[22:23], v[6:9], off
	s_nop 1
	v_pk_mul_f32 v[8:9], v[10:11], v[20:21] op_sel_hi:[1,0]
	v_pk_mul_f32 v[6:7], v[12:13], v[20:21] op_sel_hi:[1,0]
	global_store_dwordx4 v[22:23], v[6:9], off offset:64
	s_branch .LBB0_672
